# collective copy engines at P2/P5/P7 move 16 groups (128 KiB) per grab; grabs that straddle the K/V tensor boundary or the end are handled
# baseline (speedup 1.0000x reference)
.LBB0_175:
	s_nop 0
	v_readlane_b32 s4, v242, 2
	v_readlane_b32 s6, v242, 4
	v_readlane_b32 s7, v242, 5
	s_add_u32 s0, s6, 0x2000
	s_addc_u32 s1, s7, 0
	v_readlane_b32 s5, v242, 3
	v_writelane_b32 v242, s0, 43
	v_lshlrev_b32_e32 v148, 4, v0
	s_nop 0
	v_writelane_b32 v242, s1, 44
	s_add_u32 s0, s6, 0x6200000
	s_addc_u32 s1, s7, 0
	v_writelane_b32 v242, s0, 45
	s_nop 1
	v_writelane_b32 v242, s1, 46
	s_add_u32 s0, s6, 0xa400000
	s_addc_u32 s1, s7, 0
	v_writelane_b32 v242, s0, 47
	s_nop 1
	v_writelane_b32 v242, s1, 48
	s_add_u32 s0, s6, 0x2d500000
	s_addc_u32 s1, s7, 0
	v_writelane_b32 v242, s0, 49
	s_nop 1
	v_writelane_b32 v242, s1, 50
	s_add_u32 s0, s6, 0x2f600000
	s_addc_u32 s1, s7, 0
	v_writelane_b32 v242, s0, 51
	s_nop 1
	v_writelane_b32 v242, s1, 52
	s_add_u32 s0, s6, 0x31700000
	s_addc_u32 s1, s7, 0
	s_cmpk_eq_i32 s84, 0x100
	v_writelane_b32 v242, s0, 53
	s_cselect_b64 s[58:59], -1, 0
	s_cmp_lt_i32 s72, 3
	v_writelane_b32 v242, s1, 54
	s_cselect_b64 s[0:1], -1, 0
	s_cmp_gt_i32 s73, 2
	s_cselect_b64 s[2:3], -1, 0
	s_and_b64 s[0:1], s[0:1], s[2:3]
	v_writelane_b32 v242, s92, 55
	s_andn2_b64 vcc, exec, s[0:1]
	s_mov_b32 s0, s84
	v_writelane_b32 v242, s93, 56
	v_writelane_b32 v242, s0, 57
	v_writelane_b32 v241, s58, 0
	s_nop 0
	v_writelane_b32 v242, s1, 58
	v_writelane_b32 v242, s72, 59
	s_mov_b32 s0, s88
	v_writelane_b32 v241, s59, 1
	v_writelane_b32 v242, s73, 60
	v_writelane_b32 v242, s0, 61
	s_nop 1
	v_writelane_b32 v242, s1, 62
	v_writelane_b32 v242, s74, 63
	s_cbranch_vccnz .LBB0_607
	s_and_b64 s[0:1], s[58:59], exec
	s_cselect_b32 s33, 0xd8, s84
	s_add_u32 s0, s6, 0x5400
	s_addc_u32 s1, s7, 0
	v_writelane_b32 v241, s0, 2
	v_mov_b32_e32 v149, 0
	v_lshl_add_u64 v[152:153], s[4:5], 0, v[148:149]
	v_writelane_b32 v241, s1, 3
	s_add_u32 s0, s6, 0x5500
	s_addc_u32 s1, s7, 0
	v_writelane_b32 v241, s0, 4
	s_nop 1
	v_writelane_b32 v241, s1, 5
	s_add_u32 s0, s6, 0x5600
	s_addc_u32 s1, s7, 0
	v_writelane_b32 v241, s0, 6
	s_nop 1
	v_writelane_b32 v241, s1, 7
	s_add_u32 s0, s6, 0x5700
	s_addc_u32 s1, s7, 0
	v_writelane_b32 v241, s0, 8
	s_nop 1
	v_writelane_b32 v241, s1, 9
	s_add_u32 s0, s6, 0x5800
	s_addc_u32 s1, s7, 0
	v_writelane_b32 v241, s0, 10
	s_nop 1
	v_writelane_b32 v241, s1, 11
	s_add_u32 s0, s6, 0x5900
	s_addc_u32 s1, s7, 0
	s_add_u32 s34, s6, 0x5a00
	s_addc_u32 s35, s7, 0
	s_add_u32 s40, s6, 0x5b00
	s_addc_u32 s41, s7, 0
	s_add_u32 s42, s6, 0x5c00
	s_addc_u32 s43, s7, 0
	s_add_u32 s50, s6, 0x5d00
	s_addc_u32 s51, s7, 0
	s_add_u32 s56, s6, 0x5e00
	s_addc_u32 s57, s7, 0
	s_add_u32 s60, s6, 0x5f00
	s_addc_u32 s61, s7, 0
	s_add_u32 s62, s6, 0x6000
	s_addc_u32 s63, s7, 0
	s_add_u32 s64, s6, 0x6100
	s_addc_u32 s65, s7, 0
	s_add_u32 s68, s6, 0x6200
	s_addc_u32 s69, s7, 0
	s_add_u32 s70, s6, 0x6300
	s_addc_u32 s71, s7, 0
	s_ashr_i32 s54, s33, 31
	v_writelane_b32 v241, s0, 12
	s_cmp_gt_u32 s73, 3
	s_nop 0
	v_writelane_b32 v241, s1, 13
	s_cselect_b64 s[0:1], -1, 0
	v_writelane_b32 v241, s0, 14
	s_cmp_lt_i32 s92, s33
	s_nop 0
	v_writelane_b32 v241, s1, 15
	s_mov_b64 s[0:1], -1
	s_cbranch_scc1 .LBB0_210
	v_lshlrev_b32_e32 v104, 4, v0
	v_add_u32_e32 v105, 0x2000, v104
	v_add_u32_e32 v106, 0x4000, v104
	v_add_u32_e32 v107, 0x6000, v104
	v_add_u32_e32 v108, 0x8000, v104
	v_add_u32_e32 v109, 0xa000, v104
	v_add_u32_e32 v110, 0xc000, v104
	v_add_u32_e32 v111, 0xe000, v104
	v_add_u32_e32 v112, 0x10000, v104
	v_add_u32_e32 v113, 0x12000, v104
	v_add_u32_e32 v114, 0x14000, v104
	v_add_u32_e32 v115, 0x16000, v104
	v_add_u32_e32 v116, 0x18000, v104
	v_add_u32_e32 v117, 0x1a000, v104
	v_add_u32_e32 v118, 0x1c000, v104
	v_add_u32_e32 v119, 0x1e000, v104
	v_lshrrev_b32_e32 v5, 6, v0
	v_readlane_b32 s56, v242, 43
	v_readlane_b32 s57, v242, 44
	v_readlane_b32 s60, v242, 2
	v_readlane_b32 s61, v242, 3
	v_readlane_b32 s66, v242, 4
	v_readlane_b32 s67, v242, 5
	v_readlane_b32 s68, v242, 25
	v_readfirstlane_b32 s70, v5
	v_mov_b32_e32 v2, 0
	v_mov_b32_e32 v3, 16
	v_mov_b32_e32 v6, 0x20180
	s_mov_b32 s64, 0x10478000
	s_mov_b32 s65, 0x30478000
	s_add_u32 s66, s66, 0x5400
	s_addc_u32 s67, s67, 0
	s_mul_i32 s68, s68, s84
	s_mov_b64 s[62:63], exec
	s_mov_b32 s71, 0
	s_cmp_lg_u32 s70, 0
	s_cbranch_scc1 .Lce_first_done_P2
	s_mov_b64 exec, 1
	global_atomic_add v4, v2, v3, s[56:57] sc0
	s_waitcnt vmcnt(0)
	ds_write_b32 v6, v4
	s_waitcnt lgkmcnt(0)
	s_mov_b64 exec, s[62:63]

.Lce_nopoll_P2:
	s_cmp_ge_u32 s4, 0xff00
	s_cselect_b32 s8, s46, s44
	s_cselect_b32 s9, s47, s45
	s_cselect_b32 s55, s65, s64
	s_cselect_b32 s52, 0xff00, 0
	s_sub_u32 s52, s4, s52
	s_mul_hi_i32 s53, s52, 0x80808081
	s_add_i32 s53, s53, s52
	s_lshr_b32 s54, s53, 31
	s_ashr_i32 s53, s53, 8
	s_add_i32 s53, s53, s54
	s_mul_i32 s54, s53, 0x1fe
	s_sub_u32 s54, s52, s54
	s_sub_u32 s75, 0x1fe, s54
	s_lshl_b32 s53, s53, 22
	s_lshl_b32 s54, s54, 13
	s_add_u32 s53, s53, s54
	s_add_u32 s55, s55, s53
	s_add_u32 s53, s53, 0x4000
	s_add_u32 s8, s8, s53
	s_addc_u32 s9, s9, 0
	s_add_u32 s10, s60, s55
	s_addc_u32 s11, s61, 0
	s_add_u32 s12, s8, 0x4000
	s_addc_u32 s13, s9, 0
	s_add_u32 s50, s10, 0x4000
	s_addc_u32 s51, s11, 0
	s_cmp_lt_u32 s52, 0xfd02
	s_cbranch_scc1 .Lce_ord_P2
	s_lshl_b32 s54, s75, 13
	s_cmp_ge_u32 s4, 0xff00
	s_cbranch_scc1 .Lce_endv_P2
	s_add_u32 s12, s46, 0x4000
	s_addc_u32 s13, s47, 0
	s_sub_u32 s12, s12, s54
	s_subb_u32 s13, s13, 0
	s_add_u32 s50, s60, s65
	s_addc_u32 s51, s61, 0
	s_sub_u32 s50, s50, s54
	s_subb_u32 s51, s51, 0
	s_branch .Lce_ord_P2
.Lce_endv_P2:
	s_sub_u32 s12, s8, s54
	s_subb_u32 s13, s9, 0
	s_sub_u32 s50, s10, s54
	s_subb_u32 s51, s11, 0
.Lce_ord_P2:
	s_cmp_le_u32 s75, 0
	s_cselect_b32 s6, s12, s8
	s_cselect_b32 s7, s13, s9
	global_load_dwordx4 v[40:43], v104, s[6:7] nt
	s_cmp_le_u32 s75, 1
	s_cselect_b32 s6, s12, s8
	s_cselect_b32 s7, s13, s9
	global_load_dwordx4 v[44:47], v105, s[6:7] nt
	s_cmp_le_u32 s75, 2
	s_cselect_b32 s6, s12, s8
	s_cselect_b32 s7, s13, s9
	global_load_dwordx4 v[48:51], v106, s[6:7] nt
	s_cmp_le_u32 s75, 3
	s_cselect_b32 s6, s12, s8
	s_cselect_b32 s7, s13, s9
	global_load_dwordx4 v[52:55], v107, s[6:7] nt
	s_cmp_le_u32 s75, 4
	s_cselect_b32 s6, s12, s8
	s_cselect_b32 s7, s13, s9
	global_load_dwordx4 v[56:59], v108, s[6:7] nt
	s_cmp_le_u32 s75, 5
	s_cselect_b32 s6, s12, s8
	s_cselect_b32 s7, s13, s9
	global_load_dwordx4 v[60:63], v109, s[6:7] nt
	s_cmp_le_u32 s75, 6
	s_cselect_b32 s6, s12, s8
	s_cselect_b32 s7, s13, s9
	global_load_dwordx4 v[64:67], v110, s[6:7] nt
	s_cmp_le_u32 s75, 7
	s_cselect_b32 s6, s12, s8
	s_cselect_b32 s7, s13, s9
	global_load_dwordx4 v[68:71], v111, s[6:7] nt
	s_cmp_le_u32 s75, 8
	s_cselect_b32 s6, s12, s8
	s_cselect_b32 s7, s13, s9
	global_load_dwordx4 v[72:75], v112, s[6:7] nt
	s_cmp_le_u32 s75, 9
	s_cselect_b32 s6, s12, s8
	s_cselect_b32 s7, s13, s9
	global_load_dwordx4 v[76:79], v113, s[6:7] nt
	s_cmp_le_u32 s75, 10
	s_cselect_b32 s6, s12, s8
	s_cselect_b32 s7, s13, s9
	global_load_dwordx4 v[80:83], v114, s[6:7] nt
	s_cmp_le_u32 s75, 11
	s_cselect_b32 s6, s12, s8
	s_cselect_b32 s7, s13, s9
	global_load_dwordx4 v[84:87], v115, s[6:7] nt
	s_cmp_le_u32 s75, 12
	s_cselect_b32 s6, s12, s8
	s_cselect_b32 s7, s13, s9
	global_load_dwordx4 v[88:91], v116, s[6:7] nt
	s_cmp_le_u32 s75, 13
	s_cselect_b32 s6, s12, s8
	s_cselect_b32 s7, s13, s9
	global_load_dwordx4 v[92:95], v117, s[6:7] nt
	s_cmp_le_u32 s75, 14
	s_cselect_b32 s6, s12, s8
	s_cselect_b32 s7, s13, s9
	global_load_dwordx4 v[96:99], v118, s[6:7] nt
	s_cmp_le_u32 s75, 15
	s_cselect_b32 s6, s12, s8
	s_cselect_b32 s7, s13, s9
	global_load_dwordx4 v[100:103], v119, s[6:7] nt
	s_mov_b32 s77, -1
	s_cmp_lg_u32 s70, 0
	s_cbranch_scc1 .Lce_wait_all_P2
	s_waitcnt vmcnt(16)
	s_mov_b64 exec, 1
	v_add_u32_e32 v8, v8, v9
	v_add_u32_e32 v8, v8, v10
	v_add_u32_e32 v8, v8, v11
	v_add_u32_e32 v8, v8, v12
	v_add_u32_e32 v8, v8, v13
	v_add_u32_e32 v8, v8, v14
	v_add_u32_e32 v8, v8, v15
	v_add_u32_e32 v8, v8, v16
	v_add_u32_e32 v8, v8, v17
	v_add_u32_e32 v8, v8, v18
	v_add_u32_e32 v8, v8, v19
	v_add_u32_e32 v8, v8, v20
	v_add_u32_e32 v8, v8, v21
	v_add_u32_e32 v8, v8, v22
	v_add_u32_e32 v8, v8, v23
	s_nop 1
	v_readfirstlane_b32 s69, v8
	s_nop 3
	s_sub_u32 s69, s69, s68
	s_cmp_ge_u32 s69, 16
	s_cbranch_scc1 .Lce_stop_P2
	global_atomic_add v4, v2, v3, s[56:57] sc0
	s_mov_b64 exec, s[62:63]
	s_waitcnt vmcnt(1)
	s_mov_b32 s77, 0
	s_branch .Lce_stores_P2

.Lce_stores_P2:
	s_cmp_le_u32 s75, 0
	s_cselect_b32 s6, s50, s10
	s_cselect_b32 s7, s51, s11
	global_store_dwordx4 v104, v[40:43], s[6:7] nt
	s_cmp_le_u32 s75, 1
	s_cselect_b32 s6, s50, s10
	s_cselect_b32 s7, s51, s11
	global_store_dwordx4 v105, v[44:47], s[6:7] nt
	s_cmp_le_u32 s75, 2
	s_cselect_b32 s6, s50, s10
	s_cselect_b32 s7, s51, s11
	global_store_dwordx4 v106, v[48:51], s[6:7] nt
	s_cmp_le_u32 s75, 3
	s_cselect_b32 s6, s50, s10
	s_cselect_b32 s7, s51, s11
	global_store_dwordx4 v107, v[52:55], s[6:7] nt
	s_cmp_le_u32 s75, 4
	s_cselect_b32 s6, s50, s10
	s_cselect_b32 s7, s51, s11
	global_store_dwordx4 v108, v[56:59], s[6:7] nt
	s_cmp_le_u32 s75, 5
	s_cselect_b32 s6, s50, s10
	s_cselect_b32 s7, s51, s11
	global_store_dwordx4 v109, v[60:63], s[6:7] nt
	s_cmp_le_u32 s75, 6
	s_cselect_b32 s6, s50, s10
	s_cselect_b32 s7, s51, s11
	global_store_dwordx4 v110, v[64:67], s[6:7] nt
	s_cmp_le_u32 s75, 7
	s_cselect_b32 s6, s50, s10
	s_cselect_b32 s7, s51, s11
	global_store_dwordx4 v111, v[68:71], s[6:7] nt
	s_cmp_le_u32 s75, 8
	s_cselect_b32 s6, s50, s10
	s_cselect_b32 s7, s51, s11
	global_store_dwordx4 v112, v[72:75], s[6:7] nt
	s_cmp_le_u32 s75, 9
	s_cselect_b32 s6, s50, s10
	s_cselect_b32 s7, s51, s11
	global_store_dwordx4 v113, v[76:79], s[6:7] nt
	s_cmp_le_u32 s75, 10
	s_cselect_b32 s6, s50, s10
	s_cselect_b32 s7, s51, s11
	global_store_dwordx4 v114, v[80:83], s[6:7] nt
	s_cmp_le_u32 s75, 11
	s_cselect_b32 s6, s50, s10
	s_cselect_b32 s7, s51, s11
	global_store_dwordx4 v115, v[84:87], s[6:7] nt
	s_cmp_le_u32 s75, 12
	s_cselect_b32 s6, s50, s10
	s_cselect_b32 s7, s51, s11
	global_store_dwordx4 v116, v[88:91], s[6:7] nt
	s_cmp_le_u32 s75, 13
	s_cselect_b32 s6, s50, s10
	s_cselect_b32 s7, s51, s11
	global_store_dwordx4 v117, v[92:95], s[6:7] nt
	s_cmp_le_u32 s75, 14
	s_cselect_b32 s6, s50, s10
	s_cselect_b32 s7, s51, s11
	global_store_dwordx4 v118, v[96:99], s[6:7] nt
	s_cmp_le_u32 s75, 15
	s_cselect_b32 s6, s50, s10
	s_cselect_b32 s7, s51, s11
	global_store_dwordx4 v119, v[100:103], s[6:7] nt
	s_cmp_lg_u32 s70, 0
	s_cbranch_scc1 .Lce_bar_P2
	s_cmp_lg_u32 s77, 0
	s_cbranch_scc1 .Lce_pub_P2
	s_waitcnt vmcnt(16)
	s_branch .Lce_pub2_P2

.LBB0_1752:
	s_nop 0
	v_readlane_b32 s4, v242, 2
	v_readlane_b32 s6, v242, 4
	v_readlane_b32 s7, v242, 5
	s_add_u32 s0, s6, 0x14900000
	s_addc_u32 s1, s7, 0
	v_readlane_b32 s5, v242, 3
	v_writelane_b32 v242, s0, 47
	s_cmp_lt_i32 s72, 6
	s_nop 0
	v_writelane_b32 v242, s1, 48
	s_cselect_b64 s[0:1], -1, 0
	s_cmp_gt_i32 s73, 5
	s_cselect_b64 s[2:3], -1, 0
	s_and_b64 s[0:1], s[0:1], s[2:3]
	s_andn2_b64 vcc, exec, s[0:1]
	s_cbranch_vccnz .LBB0_1891
	s_and_b64 s[0:1], s[58:59], exec
	s_cselect_b32 s33, 0xb0, s84
	s_add_u32 s0, s6, 0x5400
	s_addc_u32 s1, s7, 0
	v_writelane_b32 v242, s0, 30
	v_mov_b32_e32 v149, 0
	v_lshl_add_u64 v[134:135], s[4:5], 0, v[148:149]
	v_writelane_b32 v242, s1, 31
	s_add_u32 s0, s6, 0x5500
	s_addc_u32 s1, s7, 0
	v_writelane_b32 v241, s0, 2
	s_mov_b64 s[4:5], -1
	s_nop 0
	v_writelane_b32 v241, s1, 3
	s_add_u32 s0, s6, 0x5600
	s_addc_u32 s1, s7, 0
	v_writelane_b32 v241, s0, 4
	s_nop 1
	v_writelane_b32 v241, s1, 5
	s_add_u32 s0, s6, 0x5700
	s_addc_u32 s1, s7, 0
	v_writelane_b32 v241, s0, 6
	s_nop 1
	v_writelane_b32 v241, s1, 7
	s_add_u32 s0, s6, 0x5800
	s_addc_u32 s1, s7, 0
	s_add_u32 s14, s6, 0x5900
	s_addc_u32 s15, s7, 0
	s_add_u32 s16, s6, 0x5a00
	s_addc_u32 s17, s7, 0
	s_add_u32 s18, s6, 0x5b00
	s_addc_u32 s19, s7, 0
	s_add_u32 s20, s6, 0x5c00
	s_addc_u32 s21, s7, 0
	s_add_u32 s22, s6, 0x5d00
	s_addc_u32 s23, s7, 0
	s_add_u32 s24, s6, 0x5e00
	s_addc_u32 s25, s7, 0
	s_add_u32 s26, s6, 0x5f00
	s_addc_u32 s27, s7, 0
	s_add_u32 s28, s6, 0x6000
	s_addc_u32 s29, s7, 0
	s_add_u32 s30, s6, 0x6100
	s_addc_u32 s31, s7, 0
	s_add_u32 s34, s6, 0x6200
	s_addc_u32 s35, s7, 0
	s_add_u32 s40, s6, 0x6300
	s_addc_u32 s41, s7, 0
	s_ashr_i32 s42, s33, 31
	v_writelane_b32 v241, s0, 8
	s_cmp_gt_u32 s73, 6
	s_nop 0
	v_writelane_b32 v241, s1, 9
	s_cselect_b64 s[0:1], -1, 0
	v_writelane_b32 v241, s0, 10
	s_cmp_lt_i32 s92, s33
	s_nop 0
	v_writelane_b32 v241, s1, 11
	s_cbranch_scc1 .LBB0_1787
	v_lshlrev_b32_e32 v104, 4, v0
	v_add_u32_e32 v105, 0x2000, v104
	v_add_u32_e32 v106, 0x4000, v104
	v_add_u32_e32 v107, 0x6000, v104
	v_add_u32_e32 v108, 0x8000, v104
	v_add_u32_e32 v109, 0xa000, v104
	v_add_u32_e32 v110, 0xc000, v104
	v_add_u32_e32 v111, 0xe000, v104
	v_add_u32_e32 v112, 0x10000, v104
	v_add_u32_e32 v113, 0x12000, v104
	v_add_u32_e32 v114, 0x14000, v104
	v_add_u32_e32 v115, 0x16000, v104
	v_add_u32_e32 v116, 0x18000, v104
	v_add_u32_e32 v117, 0x1a000, v104
	v_add_u32_e32 v118, 0x1c000, v104
	v_add_u32_e32 v119, 0x1e000, v104
	v_lshrrev_b32_e32 v5, 6, v0
	v_readlane_b32 s56, v242, 43
	v_readlane_b32 s57, v242, 44
	v_readlane_b32 s60, v242, 2
	v_readlane_b32 s61, v242, 3
	v_readlane_b32 s66, v242, 4
	v_readlane_b32 s67, v242, 5
	v_readlane_b32 s68, v242, 25
	v_readfirstlane_b32 s70, v5
	v_mov_b32_e32 v2, 0
	v_mov_b32_e32 v3, 16
	v_mov_b32_e32 v6, 0x20180
	s_mov_b32 s64, 0x10478000
	s_mov_b32 s65, 0x30478000
	s_add_u32 s66, s66, 0x5400
	s_addc_u32 s67, s67, 0
	s_mul_i32 s68, s68, s84
	s_mov_b64 s[62:63], exec
	s_mov_b32 s71, 0
	s_cmp_lg_u32 s70, 0
	s_cbranch_scc1 .Lce_first_done_P5
	s_mov_b64 exec, 1
	global_atomic_add v4, v2, v3, s[56:57] sc0
	s_waitcnt vmcnt(0)
	ds_write_b32 v6, v4
	s_waitcnt lgkmcnt(0)
	s_mov_b64 exec, s[62:63]

.LBB0_1957:
	s_nop 0
	v_readlane_b32 s8, v242, 2
	v_readlane_b32 s10, v242, 4
	v_readlane_b32 s11, v242, 5
	s_add_u32 s2, s10, 0x1cd00000
	s_addc_u32 s3, s11, 0
	s_cmp_lt_i32 s72, 8
	s_cselect_b64 s[0:1], -1, 0
	s_cmp_gt_i32 s73, 7
	s_cselect_b64 s[4:5], -1, 0
	s_and_b64 s[0:1], s[0:1], s[4:5]
	v_readlane_b32 s9, v242, 3
	s_andn2_b64 vcc, exec, s[0:1]
	s_cbranch_vccnz .LBB0_2096
	s_and_b64 s[0:1], s[58:59], exec
	s_cselect_b32 s33, 0xf0, s84
	s_add_u32 s0, s10, 0x5400
	s_addc_u32 s1, s11, 0
	v_writelane_b32 v242, s0, 30
	v_mov_b32_e32 v149, 0
	v_lshl_add_u64 v[130:131], s[8:9], 0, v[148:149]
	v_writelane_b32 v242, s1, 31
	s_add_u32 s0, s10, 0x5500
	s_addc_u32 s1, s11, 0
	v_writelane_b32 v241, s0, 2
	s_mov_b64 s[4:5], -1
	s_nop 0
	v_writelane_b32 v241, s1, 3
	s_add_u32 s0, s10, 0x5600
	s_addc_u32 s1, s11, 0
	v_writelane_b32 v241, s0, 4
	s_nop 1
	v_writelane_b32 v241, s1, 5
	s_add_u32 s0, s10, 0x5700
	s_addc_u32 s1, s11, 0
	s_add_u32 s14, s10, 0x5800
	s_addc_u32 s15, s11, 0
	s_add_u32 s16, s10, 0x5900
	s_addc_u32 s17, s11, 0
	s_add_u32 s18, s10, 0x5a00
	s_addc_u32 s19, s11, 0
	s_add_u32 s20, s10, 0x5b00
	s_addc_u32 s21, s11, 0
	s_add_u32 s22, s10, 0x5c00
	s_addc_u32 s23, s11, 0
	s_add_u32 s24, s10, 0x5d00
	s_addc_u32 s25, s11, 0
	s_add_u32 s26, s10, 0x5e00
	s_addc_u32 s27, s11, 0
	s_add_u32 s28, s10, 0x5f00
	s_addc_u32 s29, s11, 0
	s_add_u32 s30, s10, 0x6000
	s_addc_u32 s31, s11, 0
	s_add_u32 s34, s10, 0x6100
	s_addc_u32 s35, s11, 0
	s_add_u32 s36, s10, 0x6200
	s_addc_u32 s37, s11, 0
	s_add_u32 s38, s10, 0x6300
	s_addc_u32 s39, s11, 0
	s_ashr_i32 s96, s33, 31
	v_writelane_b32 v241, s0, 6
	s_cmp_gt_u32 s73, 8
	s_nop 0
	v_writelane_b32 v241, s1, 7
	s_cselect_b64 s[0:1], -1, 0
	v_writelane_b32 v241, s0, 8
	s_cmp_lt_i32 s92, s33
	s_nop 0
	v_writelane_b32 v241, s1, 9
	s_cbranch_scc1 .LBB0_1992
	v_lshlrev_b32_e32 v104, 4, v0
	v_add_u32_e32 v105, 0x2000, v104
	v_add_u32_e32 v106, 0x4000, v104
	v_add_u32_e32 v107, 0x6000, v104
	v_add_u32_e32 v108, 0x8000, v104
	v_add_u32_e32 v109, 0xa000, v104
	v_add_u32_e32 v110, 0xc000, v104
	v_add_u32_e32 v111, 0xe000, v104
	v_add_u32_e32 v112, 0x10000, v104
	v_add_u32_e32 v113, 0x12000, v104
	v_add_u32_e32 v114, 0x14000, v104
	v_add_u32_e32 v115, 0x16000, v104
	v_add_u32_e32 v116, 0x18000, v104
	v_add_u32_e32 v117, 0x1a000, v104
	v_add_u32_e32 v118, 0x1c000, v104
	v_add_u32_e32 v119, 0x1e000, v104
	v_lshrrev_b32_e32 v5, 6, v0
	v_readlane_b32 s56, v242, 43
	v_readlane_b32 s57, v242, 44
	v_readlane_b32 s60, v242, 2
	v_readlane_b32 s61, v242, 3
	v_readlane_b32 s66, v242, 4
	v_readlane_b32 s67, v242, 5
	v_readlane_b32 s68, v242, 25
	v_readfirstlane_b32 s70, v5
	v_mov_b32_e32 v2, 0
	v_mov_b32_e32 v3, 16
	v_mov_b32_e32 v6, 0x20180
	s_mov_b32 s64, 0x10478000
	s_mov_b32 s65, 0x30478000
	s_add_u32 s66, s66, 0x5400
	s_addc_u32 s67, s67, 0
	s_mul_i32 s68, s68, s84
	s_mov_b64 s[62:63], exec
	s_mov_b32 s71, 0
	s_cmp_lg_u32 s70, 0
	s_cbranch_scc1 .Lce_first_done_P7
	s_mov_b64 exec, 1
	global_atomic_add v4, v2, v3, s[56:57] sc0
	s_waitcnt vmcnt(0)
	ds_write_b32 v6, v4
	s_waitcnt lgkmcnt(0)
	s_mov_b64 exec, s[62:63]
